# counted vmcnt waits + global loads in GLA and RWKV chunk loops
# speedup vs baseline: 1.0129x; 1.0129x over previous
; #define LAS __attribute__((address_space(3)))
; __device__ __forceinline__ unsigned cvt_pk_bf16(float lo, float hi) { const f32x2_t v = {lo, hi}; const bf16x2_t b = __builtin_convertvector(v, bf16x2_t); return __builtin_bit_cast(unsigned, b); }
; #define LBAR() do { asm volatile("s_waitcnt lgkmcnt(0)" ::: "memory"); __builtin_amdgcn_s_barrier(); asm volatile("" ::: "memory"); } while (0)
; __device__ void rwkv_chunk_phase(const Params& p, int l, LAS unsigned char* lds) {
;     ...
;         RW_LOAD(dir ? 63 : 0);
;         int cur = 0;
; #pragma unroll 1
;         for (int ci = 0; ci < 64; ++ci) {
;             const int c = dir ? 63 - ci : ci; const size_t t0 = (size_t)b * SEQ_ + c * 32;
;             LBAR();
;             f32x4 lw4, kk4, b4, kd4, r4, v4;
;             for (int rp_ = 0; rp_ < STG_REP; ++rp_) {
;             if (rp_) LBAR();
; #pragma unroll
;             for (int hf = 0; hf < 2; ++hf) { float fc[8], fp[8], fn[8]; unpack8(rc[hf], fc); unpack8(rp[hf], fp); unpack8(rn[hf], fn);
;                 const f32x4 m0 = *(const LAS f32x4*)(mu_s + cg * 16 + hf * 8), m1 = *(const LAS f32x4*)(mu_s + cg * 16 + hf * 8 + 4);
;                 f32x4 x0, x1;
; #pragma unroll
;                 for (int j = 0; j < 4; ++j) { x0[j] = fc[j] + m0[j] * (0.5f * (fp[j] + fn[j]) - fc[j]); x1[j] = fc[4 + j] + m1[j] * (0.5f * (fp[4 + j] + fn[4 + j]) - fc[4 + j]); }
;                 *(LAS f32x4*)(sh_s + tok * 256 + cg * 16 + hf * 8) = x0; *(LAS f32x4*)(sh_s + tok * 256 + cg * 16 + hf * 8 + 4) = x1; }
;     ...
;             {   const f32x4 yv = *(const LAS f32x4*)(y_s + tok * 64 + cg * 4);
;                 u32x2 wv2; wv2.x = cvt_pk_bf16(yv[0], yv[1]); wv2.y = cvt_pk_bf16(yv[2], yv[3]);
;                 *(u32x2*)(Y + (t0 + tokm) * 512 + h * 64 + cg * 4) = wv2; }
.LBB0_315:
	s_or_b64 exec, exec, s[22:23]
	s_ashr_i32 s6, s86, 4
	s_and_b64 s[8:9], s[4:5], exec
	v_cndmask_b32_e64 v52, v74, v80, s[4:5]
	s_cselect_b32 s7, 0x7e0, 0
	v_add_u32_e32 v24, s7, v52
	s_ashr_i32 s7, s6, 31
	s_lshl_b64 s[60:61], s[6:7], 11
	v_ashrrev_i32_e32 v25, 31, v24
	v_lshl_add_u64 v[2:3], s[60:61], 0, v[24:25]
	v_mov_b64_e32 v[8:9], s[42:43]
	v_mad_u64_u32 v[8:9], s[6:7], v2, s46, v[8:9]
	v_mad_i32_i24 v9, v3, s46, v9
	v_lshl_add_u64 v[2:3], v[0:1], 1, v[8:9]
	global_load_dwordx4 v[8:11], v[2:3], off
	global_load_dwordx4 v[12:15], v[2:3], off offset:16
	v_mov_b32_e32 v18, v1
	v_mov_b32_e32 v19, v1
	v_mov_b32_e32 v16, v1
	v_mov_b32_e32 v17, v1
	v_mov_b64_e32 v[22:23], v[18:19]
	v_cmp_lt_i32_e32 vcc, 0, v24
	v_mov_b64_e32 v[20:21], v[16:17]
	s_and_saveexec_b64 s[6:7], vcc
	s_cbranch_execz .LBB0_317
	v_add_co_u32_e32 v16, vcc, 0xfffff240, v2
	s_nop 1
	v_addc_co_u32_e32 v17, vcc, -1, v3, vcc
	v_add_co_u32_e32 v20, vcc, 0xfffff250, v2
	s_nop 1
	v_addc_co_u32_e32 v21, vcc, -1, v3, vcc
	global_load_dwordx4 v[16:19], v[16:17], off
	s_nop 0
	global_load_dwordx4 v[20:23], v[20:21], off
.LBB0_317:
	s_or_b64 exec, exec, s[6:7]
	v_cmp_gt_i32_e32 vcc, s75, v24
	v_mov_b32_e32 v24, 0
	v_mov_b32_e32 v25, 0
	v_mov_b32_e32 v26, 0
	v_mov_b32_e32 v27, 0
	v_mov_b32_e32 v28, 0
	v_mov_b32_e32 v29, 0
	v_mov_b32_e32 v30, 0
	v_mov_b32_e32 v31, 0
	s_and_saveexec_b64 s[6:7], vcc
	s_cbranch_execz .LBB0_319
	global_load_dwordx4 v[24:27], v[2:3], off offset:3520
	global_load_dwordx4 v[28:31], v[2:3], off offset:3536
.LBB0_319:
	s_or_b64 exec, exec, s[6:7]
	s_lshl_b32 s8, s62, 2
	v_readlane_b32 s9, v254, 43
	s_add_u32 s40, s9, s8
	v_readlane_b32 s8, v254, 45
	s_addc_u32 s41, s8, 0
	s_lshl_b32 s8, s62, 7
	s_add_u32 s8, s20, s8
	s_addc_u32 s9, s21, 0
	v_mov_b32_e32 v51, v1
	v_lshl_add_u64 v[56:57], s[8:9], 0, v[50:51]
	v_readlane_b32 s8, v254, 55
	v_lshl_add_u64 v[54:55], v[0:1], 1, s[42:43]
	v_or_b32_e32 v0, s64, v72
	v_readlane_b32 s9, v254, 56
	v_cmp_eq_u32_e64 s[6:7], 0, v0
	v_cndmask_b32_e64 v0, 0, 1, s[76:77]
	v_cndmask_b32_e64 v2, 0, 1, s[8:9]
	s_or_b64 vcc, s[70:71], s[4:5]
	v_cndmask_b32_e32 v3, v2, v0, vcc
	v_and_b32_e32 v3, 1, v3
	v_cmp_eq_u32_e64 s[8:9], 1, v3
	v_cndmask_b32_e32 v3, v157, v109, vcc
	v_cmp_lt_u32_e64 s[10:11], v3, v108
	v_cndmask_b32_e64 v3, 0, 1, s[44:45]
	v_cndmask_b32_e64 v32, 0, 1, s[58:59]
	v_cndmask_b32_e32 v33, v32, v3, vcc
	v_and_b32_e32 v33, 1, v33
	v_cmp_eq_u32_e64 s[12:13], 1, v33
	v_cndmask_b32_e64 v33, 0, 1, s[34:35]
	v_cndmask_b32_e64 v34, 0, 1, s[82:83]
	v_cndmask_b32_e32 v35, v34, v33, vcc
	s_or_b64 vcc, s[84:85], s[4:5]
	v_cndmask_b32_e32 v0, v2, v0, vcc
	v_and_b32_e32 v0, 1, v0
	v_cmp_eq_u32_e64 s[16:17], 1, v0
	v_cndmask_b32_e32 v0, v157, v109, vcc
	v_cmp_lt_u32_e64 s[18:19], v0, v108
	v_cndmask_b32_e32 v0, v32, v3, vcc
	v_and_b32_e32 v0, 1, v0
	v_cmp_eq_u32_e64 s[20:21], 1, v0
	v_cndmask_b32_e32 v0, v34, v33, vcc
	v_and_b32_e32 v35, 1, v35
	v_and_b32_e32 v0, 1, v0
	s_mov_b32 s64, 0
	v_ashrrev_i32_e32 v53, 31, v52
	v_cmp_eq_u32_e64 s[14:15], 1, v35
	v_cmp_eq_u32_e64 s[22:23], 1, v0
	s_mov_b32 s65, 62
	s_mov_b32 s63, 0
	s_waitcnt vmcnt(0)
	s_branch .LBB0_321
.LBB0_320:
	s_or_b64 exec, exec, s[24:25]
	s_waitcnt lgkmcnt(0)
	s_barrier
	s_nop 2
	ds_read_b128 v[32:35], v94 offset:29184
	s_add_i32 s65, s65, -1
	s_cmp_eq_u32 s62, 64
	s_mov_b32 s63, s62
	s_waitcnt lgkmcnt(0)
	v_cvt_pk_bf16_f32 v2, v32, v33
	v_lshlrev_b64 v[32:33], 10, v[58:59]
	v_cvt_pk_bf16_f32 v3, v34, v35
	v_lshl_add_u64 v[32:33], v[56:57], 0, v[32:33]
	global_store_dwordx2 v[32:33], v[2:3], off
	s_cbranch_scc1 .LBB0_242
.LBB0_321:
	s_waitcnt lgkmcnt(0)
	s_barrier
	ds_read_b128 v[32:35], v206 offset:17664
	ds_read_b128 v[36:39], v206 offset:17680
	s_waitcnt vmcnt(1) lgkmcnt(0)
	v_lshlrev_b32_e32 v40, 16, v16
	v_and_b32_e32 v41, 0xffff0000, v16
	v_lshlrev_b32_e32 v42, 16, v24
	v_and_b32_e32 v43, 0xffff0000, v24
	v_lshlrev_b32_e32 v2, 16, v8
	v_and_b32_e32 v3, 0xffff0000, v8
	v_pk_add_f32 v[40:41], v[40:41], v[42:43]
	v_lshlrev_b32_e32 v42, 16, v26
	v_pk_fma_f32 v[40:41], v[40:41], 0.5, v[2:3] op_sel_hi:[1,0,1] neg_lo:[0,0,1] neg_hi:[0,0,1]
	v_and_b32_e32 v43, 0xffff0000, v26
	v_pk_fma_f32 v[32:33], v[40:41], v[32:33], v[2:3]
	v_lshlrev_b32_e32 v40, 16, v18
	v_and_b32_e32 v41, 0xffff0000, v18
	v_lshlrev_b32_e32 v2, 16, v10
	v_and_b32_e32 v3, 0xffff0000, v10
	v_pk_add_f32 v[40:41], v[40:41], v[42:43]
	v_lshlrev_b32_e32 v42, 16, v25
	v_pk_fma_f32 v[40:41], v[40:41], 0.5, v[2:3] op_sel_hi:[1,0,1] neg_lo:[0,0,1] neg_hi:[0,0,1]
	v_and_b32_e32 v43, 0xffff0000, v25
	v_pk_fma_f32 v[36:37], v[40:41], v[36:37], v[2:3]
	v_lshlrev_b32_e32 v40, 16, v17
	v_and_b32_e32 v41, 0xffff0000, v17
	v_lshlrev_b32_e32 v2, 16, v9
	v_and_b32_e32 v3, 0xffff0000, v9
	v_pk_add_f32 v[40:41], v[40:41], v[42:43]
	v_lshlrev_b32_e32 v42, 16, v27
	v_pk_fma_f32 v[40:41], v[40:41], 0.5, v[2:3] op_sel_hi:[1,0,1] neg_lo:[0,0,1] neg_hi:[0,0,1]
	v_and_b32_e32 v43, 0xffff0000, v27
	v_pk_fma_f32 v[34:35], v[40:41], v[34:35], v[2:3]
	v_lshlrev_b32_e32 v40, 16, v19
	v_and_b32_e32 v41, 0xffff0000, v19
	v_lshlrev_b32_e32 v2, 16, v11
	v_and_b32_e32 v3, 0xffff0000, v11
	v_pk_add_f32 v[40:41], v[40:41], v[42:43]
	v_lshlrev_b32_e32 v42, 16, v28
	v_pk_fma_f32 v[40:41], v[40:41], 0.5, v[2:3] op_sel_hi:[1,0,1] neg_lo:[0,0,1] neg_hi:[0,0,1]
	v_and_b32_e32 v43, 0xffff0000, v28
	v_pk_fma_f32 v[38:39], v[40:41], v[38:39], v[2:3]
	ds_write_b128 v87, v[32:35]
	ds_write_b128 v87, v[36:39] offset:16
	ds_read_b128 v[32:35], v206 offset:17696
	ds_read_b128 v[36:39], v206 offset:17712
	v_lshlrev_b32_e32 v40, 16, v20
	v_and_b32_e32 v41, 0xffff0000, v20
	v_lshlrev_b32_e32 v2, 16, v12
	v_and_b32_e32 v3, 0xffff0000, v12
	v_pk_add_f32 v[40:41], v[40:41], v[42:43]
	v_lshlrev_b32_e32 v42, 16, v30
	v_pk_fma_f32 v[40:41], v[40:41], 0.5, v[2:3] op_sel_hi:[1,0,1] neg_lo:[0,0,1] neg_hi:[0,0,1]
	v_and_b32_e32 v43, 0xffff0000, v30
	s_waitcnt lgkmcnt(1)
; #define LAS __attribute__((address_space(3)))
; __device__ __forceinline__ unsigned cvt_pk_bf16(float lo, float hi) { const f32x2_t v = {lo, hi}; const bf16x2_t b = __builtin_convertvector(v, bf16x2_t); return __builtin_bit_cast(unsigned, b); }
; #define LBAR() do { asm volatile("s_waitcnt lgkmcnt(0)" ::: "memory"); __builtin_amdgcn_s_barrier(); asm volatile("" ::: "memory"); } while (0)
; __device__ void rwkv_chunk_phase(const Params& p, int l, LAS unsigned char* lds) {
;     ...
;             for (int hf = 0; hf < 2; ++hf) { float fc[8], fp[8], fn[8]; unpack8(rc[hf], fc); unpack8(rp[hf], fp); unpack8(rn[hf], fn);
;                 const f32x4 m0 = *(const LAS f32x4*)(mu_s + cg * 16 + hf * 8), m1 = *(const LAS f32x4*)(mu_s + cg * 16 + hf * 8 + 4);
;                 f32x4 x0, x1;
; #pragma unroll
;                 for (int j = 0; j < 4; ++j) { x0[j] = fc[j] + m0[j] * (0.5f * (fp[j] + fn[j]) - fc[j]); x1[j] = fc[4 + j] + m1[j] * (0.5f * (fp[4 + j] + fn[4 + j]) - fc[4 + j]); }
;                 *(LAS f32x4*)(sh_s + tok * 256 + cg * 16 + hf * 8) = x0; *(LAS f32x4*)(sh_s + tok * 256 + cg * 16 + hf * 8 + 4) = x1; }
;             LBAR();
;             {   const int rt = wid >> 2, ct = wid & 3, row = rt * 16 + r16;
;                 const f32x4 d0 = *(const LAS f32x4*)(sh_s + row * 256 + 192 + quad * 8), d1 = *(const LAS f32x4*)(sh_s + row * 256 + 196 + quad * 8);
;                 const f32x4 e0 = *(const LAS f32x4*)(sh_s + row * 256 + 224 + quad * 8), e1 = *(const LAS f32x4*)(sh_s + row * 256 + 228 + quad * 8);
;                 u32x4 aw, aa;
;                 aw.x = cvt_pk_bf16(tanh_(d0[0]), tanh_(d0[1])); aw.y = cvt_pk_bf16(tanh_(d0[2]), tanh_(d0[3])); aw.z = cvt_pk_bf16(tanh_(d1[0]), tanh_(d1[1])); aw.w = cvt_pk_bf16(tanh_(d1[2]), tanh_(d1[3]));
;                 aa.x = cvt_pk_bf16(e0[0], e0[1]); aa.y = cvt_pk_bf16(e0[2], e0[3]); aa.z = cvt_pk_bf16(e1[0], e1[1]); aa.w = cvt_pk_bf16(e1[2], e1[3]);
;                 const bf16x8 bw = *(const LAS bf16x8*)(w2T + (ct * 16 + r16) * 40 + quad * 8), ba = *(const LAS bf16x8*)(a2T + (ct * 16 + r16) * 40 + quad * 8);
;                 const f32x4 z4 = {0.f, 0.f, 0.f, 0.f};
;                 const f32x4 cw = __builtin_amdgcn_mfma_f32_16x16x32_bf16(__builtin_bit_cast(bf16x8, aw), bw, z4, 0, 0, 0);
;                 const f32x4 ca = __builtin_amdgcn_mfma_f32_16x16x32_bf16(__builtin_bit_cast(bf16x8, aa), ba, z4, 0, 0, 0);
	v_pk_fma_f32 v[32:33], v[40:41], v[32:33], v[2:3]
	v_lshlrev_b32_e32 v40, 16, v22
	v_and_b32_e32 v41, 0xffff0000, v22
	v_lshlrev_b32_e32 v2, 16, v14
	v_and_b32_e32 v3, 0xffff0000, v14
	v_pk_add_f32 v[40:41], v[40:41], v[42:43]
	v_lshlrev_b32_e32 v42, 16, v29
	v_pk_fma_f32 v[40:41], v[40:41], 0.5, v[2:3] op_sel_hi:[1,0,1] neg_lo:[0,0,1] neg_hi:[0,0,1]
	v_and_b32_e32 v43, 0xffff0000, v29
	s_waitcnt lgkmcnt(0)
	v_pk_fma_f32 v[36:37], v[40:41], v[36:37], v[2:3]
	v_lshlrev_b32_e32 v40, 16, v21
	v_and_b32_e32 v41, 0xffff0000, v21
	v_lshlrev_b32_e32 v2, 16, v13
	v_and_b32_e32 v3, 0xffff0000, v13
	v_pk_add_f32 v[40:41], v[40:41], v[42:43]
	v_lshlrev_b32_e32 v42, 16, v31
	v_pk_fma_f32 v[40:41], v[40:41], 0.5, v[2:3] op_sel_hi:[1,0,1] neg_lo:[0,0,1] neg_hi:[0,0,1]
	v_and_b32_e32 v43, 0xffff0000, v31
	v_pk_fma_f32 v[34:35], v[40:41], v[34:35], v[2:3]
	v_lshlrev_b32_e32 v40, 16, v23
	v_and_b32_e32 v41, 0xffff0000, v23
	v_lshlrev_b32_e32 v2, 16, v15
	v_and_b32_e32 v3, 0xffff0000, v15
	v_pk_add_f32 v[40:41], v[40:41], v[42:43]
	s_add_i32 s62, s65, 1
	v_pk_fma_f32 v[40:41], v[40:41], 0.5, v[2:3] op_sel_hi:[1,0,1] neg_lo:[0,0,1] neg_hi:[0,0,1]
	s_nop 0
	v_pk_fma_f32 v[38:39], v[40:41], v[38:39], v[2:3]
	ds_write_b128 v87, v[32:35] offset:32
	ds_write_b128 v87, v[36:39] offset:48
	s_waitcnt lgkmcnt(0)
	s_barrier
	ds_read_b128 v[32:35], v89 offset:768
	ds_read_b128 v[36:39], v89 offset:784
	ds_read_b128 v[40:43], v89 offset:896
	s_waitcnt lgkmcnt(2)
	v_mul_f32_e64 v0, |v32|, -2.0
	v_mul_f32_e32 v0, 0x3fb8aa3b, v0
	v_exp_f32_e32 v2, v0
	v_mul_f32_e64 v0, |v33|, -2.0
	v_mul_f32_e32 v0, 0x3fb8aa3b, v0
	v_exp_f32_e32 v3, v0
	v_add_f32_e32 v0, 1.0, v2
	v_rcp_f32_e32 v44, v0
	v_cmp_gt_f32_e32 vcc, 0, v33
	v_add_f32_e32 v0, 1.0, v3
	v_rcp_f32_e32 v45, v0
	v_mul_f32_e64 v0, |v34|, -2.0
	v_pk_add_f32 v[2:3], v[2:3], 1.0 op_sel_hi:[1,0] neg_lo:[1,0] neg_hi:[1,0]
	v_mul_f32_e32 v0, 0x3fb8aa3b, v0
	v_pk_mul_f32 v[2:3], v[2:3], v[44:45]
	v_exp_f32_e32 v44, v0
	v_mul_f32_e64 v0, |v35|, -2.0
	v_mul_f32_e32 v0, 0x3fb8aa3b, v0
	v_exp_f32_e32 v45, v0
	v_cndmask_b32_e64 v0, v3, -v3, vcc
	v_add_f32_e32 v3, 1.0, v44
	v_cmp_gt_f32_e32 vcc, 0, v32
	v_rcp_f32_e32 v46, v3
	v_add_f32_e32 v3, 1.0, v45
	v_cndmask_b32_e64 v2, v2, -v2, vcc
	v_rcp_f32_e32 v47, v3
	v_cvt_pk_bf16_f32 v32, v2, v0
	s_waitcnt lgkmcnt(1)
	v_mul_f32_e64 v0, |v36|, -2.0
	v_mul_f32_e32 v0, 0x3fb8aa3b, v0
	v_pk_add_f32 v[2:3], v[44:45], 1.0 op_sel_hi:[1,0] neg_lo:[1,0] neg_hi:[1,0]
	v_exp_f32_e32 v44, v0
	v_mul_f32_e64 v0, |v37|, -2.0
	v_mul_f32_e32 v0, 0x3fb8aa3b, v0
	v_pk_mul_f32 v[2:3], v[2:3], v[46:47]
	v_exp_f32_e32 v45, v0
	v_cmp_gt_f32_e32 vcc, 0, v35
	s_waitcnt lgkmcnt(0)
	v_cvt_pk_bf16_f32 v40, v40, v41
	v_cvt_pk_bf16_f32 v41, v42, v43
	v_cndmask_b32_e64 v0, v3, -v3, vcc
	v_cmp_gt_f32_e32 vcc, 0, v34
	v_add_f32_e32 v3, 1.0, v44
	v_rcp_f32_e32 v46, v3
	v_cndmask_b32_e64 v2, v2, -v2, vcc
	v_cvt_pk_bf16_f32 v33, v2, v0
	v_mul_f32_e64 v0, |v38|, -2.0
	v_add_f32_e32 v3, 1.0, v45
	v_mul_f32_e32 v0, 0x3fb8aa3b, v0
	v_rcp_f32_e32 v47, v3
	v_pk_add_f32 v[2:3], v[44:45], 1.0 op_sel_hi:[1,0] neg_lo:[1,0] neg_hi:[1,0]
	v_exp_f32_e32 v44, v0
	v_mul_f32_e64 v0, |v39|, -2.0
	v_mul_f32_e32 v0, 0x3fb8aa3b, v0
	v_exp_f32_e32 v45, v0
	v_pk_mul_f32 v[2:3], v[2:3], v[46:47]
	v_cmp_gt_f32_e32 vcc, 0, v37
	s_nop 1
	v_cndmask_b32_e64 v0, v3, -v3, vcc
	v_add_f32_e32 v3, 1.0, v44
	v_rcp_f32_e32 v46, v3
	v_add_f32_e32 v3, 1.0, v45
	v_rcp_f32_e32 v47, v3
	v_cmp_gt_f32_e32 vcc, 0, v36
	s_nop 1
	v_cndmask_b32_e64 v2, v2, -v2, vcc
	v_cvt_pk_bf16_f32 v34, v2, v0
	v_pk_add_f32 v[2:3], v[44:45], 1.0 op_sel_hi:[1,0] neg_lo:[1,0] neg_hi:[1,0]
	v_cmp_gt_f32_e32 vcc, 0, v39
	v_pk_mul_f32 v[2:3], v[2:3], v[46:47]
	s_nop 0
	v_cndmask_b32_e64 v0, v3, -v3, vcc
	v_cmp_gt_f32_e32 vcc, 0, v38
	ds_read_b128 v[36:39], v91
	ds_read_b128 v[44:47], v89 offset:912
	v_cndmask_b32_e64 v2, v2, -v2, vcc
	v_cvt_pk_bf16_f32 v35, v2, v0
	ds_read_b128 v[58:61], v91 offset:5120
	ds_read2st64_b32 v[2:3], v207 offset0:64 offset1:65
	s_waitcnt lgkmcnt(3)
	v_mfma_f32_16x16x32_bf16 v[32:35], v[32:35], v[36:39], 0
	s_waitcnt lgkmcnt(2)
	v_cvt_pk_bf16_f32 v42, v44, v45
	v_cvt_pk_bf16_f32 v43, v46, v47
	s_waitcnt lgkmcnt(0)
; #define LAS __attribute__((address_space(3)))
; __device__ __forceinline__ unsigned cvt_pk_bf16(float lo, float hi) { const f32x2_t v = {lo, hi}; const bf16x2_t b = __builtin_convertvector(v, bf16x2_t); return __builtin_bit_cast(unsigned, b); }
; __device__ __forceinline__ float bf_lo(unsigned w) { return __uint_as_float(w << 16); }
; __device__ __forceinline__ float bf_hi(unsigned w) { return __uint_as_float(w & 0xffff0000u); }
; __device__ void rwkv_chunk_phase(const Params& p, int l, LAS unsigned char* lds) {
;     ...
;                 const int col = ct * 16 + r16; const float w0c = c_s[col], a0c = c_s[64 + col];
;                 f32x4 lwv, lo;
; #pragma unroll
;                 for (int j = 0; j < 4; ++j) { const int tr_ = rt * 16 + quad * 4 + j; lwv[j] = -__expf(-softplus_(-(cw[j] + w0c)) - 0.5f); y_s[tr_ * 64 + col] = lwv[j]; lg_s[tr_ * 64 + col] = ca[j] + a0c; }
;                 const unsigned h01 = cvt_pk_bf16(lwv[0], lwv[1]), h23 = cvt_pk_bf16(lwv[2], lwv[3]);
;                 lo[0] = lwv[0] - bf_lo(h01); lo[1] = lwv[1] - bf_hi(h01); lo[2] = lwv[2] - bf_lo(h23); lo[3] = lwv[3] - bf_hi(h23);
;                 u32x2 hw; hw.x = h01; hw.y = h23; *(LAS u32x2*)(lwT_hi + col * 40 + rt * 16 + quad * 4) = hw; st_bf4(lwT_lo + col * 40 + rt * 16 + quad * 4, lo); }
;             LBAR();
;             {   const f32x4 wp = *(const LAS f32x4*)(y_s + tok * 64 + j0), ap = *(const LAS f32x4*)(lg_s + tok * 64 + j0);
;                 r4 = *(const LAS f32x4*)(sh_s + tok * 256 + j0); const f32x4 kv4 = *(const LAS f32x4*)(sh_s + tok * 256 + 64 + j0); v4 = *(const LAS f32x4*)(sh_s + tok * 256 + 128 + j0);
;                 float ss = 0.f, bs = 0.f;
; #pragma unroll
;                 for (int j = 0; j < 4; ++j) { kk4[j] = kv4[j] * c_s[128 + j0 + j]; ss += kk4[j] * kk4[j]; }
;                 ss = red16d(ss);
;                 const float rn_ = rsqrtf(ss + 1e-12f);
; #pragma unroll
;                 for (int j = 0; j < 4; ++j) {
;                     const float a = sigmoid_(ap[j]);
;                     lw4[j] = wp[j];
;                     kk4[j] *= rn_; b4[j] = kk4[j] * a;
;                     kd4[j] = kv4[j] * (1.0f + (a - 1.0f) * c_s[192 + j0 + j]);
;                     bs += r4[j] * kd4[j] * c_s[256 + j0 + j];
;                 }
;                 bs = red16d(bs);
;                 if (dir == 0 && cg == 0) BON[(t0 + tokm) * 8 + h] = bs;
	s_nop 3
	v_add_f32_e32 v0, v32, v2
	v_mul_f32_e64 v32, |v0|, s97
	v_exp_f32_e32 v32, v32
	v_add_f32_e32 v33, v33, v2
	v_max_f32_e64 v0, -v0, 0
	v_add_f32_e32 v34, v34, v2
	v_add_f32_e32 v32, 1.0, v32
	v_cmp_gt_f32_e64 s[24:25], s33, v32
	v_add_f32_e32 v2, v35, v2
	v_mul_f32_e64 v35, |v2|, s97
	v_cndmask_b32_e64 v36, 0, 32, s[24:25]
	v_ldexp_f32 v32, v32, v36
	v_log_f32_e32 v32, v32
	v_mfma_f32_16x16x32_bf16 v[36:39], v[40:43], v[58:61], 0
	v_exp_f32_e32 v35, v35
	v_max_f32_e64 v2, -v2, 0
	v_mul_f32_e32 v40, 0x3f317217, v32
	v_fma_f32 v40, v32, s48, -v40
	v_fmac_f32_e32 v40, 0x3377d1cf, v32
	v_fmac_f32_e32 v40, 0x3f317217, v32
	v_cmp_lt_f32_e64 vcc, |v32|, s49
	v_add_f32_e32 v35, 1.0, v35
	v_add_f32_e32 v37, v37, v3
	v_cndmask_b32_e32 v32, v32, v40, vcc
	v_cndmask_b32_e64 v40, 0, v176, s[24:25]
	v_sub_f32_e32 v32, v32, v40
	v_mul_f32_e64 v40, |v33|, s97
	v_exp_f32_e32 v40, v40
	v_add_f32_e32 v0, v0, v32
	v_sub_f32_e32 v0, -0.5, v0
	v_mul_f32_e32 v0, 0x3fb8aa3b, v0
	v_add_f32_e32 v32, 1.0, v40
	v_cmp_gt_f32_e32 vcc, s33, v32
	v_max_f32_e64 v33, -v33, 0
	v_add_f32_e32 v38, v38, v3
	v_cndmask_b32_e64 v40, 0, 32, vcc
	v_ldexp_f32 v32, v32, v40
	v_log_f32_e32 v40, v32
	v_exp_f32_e32 v32, v0
	v_add_f32_e32 v0, v36, v3
	v_add_f32_e32 v39, v39, v3
	v_mul_f32_e32 v36, 0x3f317217, v40
	v_fma_f32 v36, v40, s48, -v36
	v_fmac_f32_e32 v36, 0x3377d1cf, v40
	v_fmac_f32_e32 v36, 0x3f317217, v40
	v_cmp_lt_f32_e64 s[24:25], |v40|, s49
	s_nop 1
	v_cndmask_b32_e64 v36, v40, v36, s[24:25]
	v_cndmask_b32_e32 v40, 0, v176, vcc
	v_sub_f32_e32 v36, v36, v40
	v_mul_f32_e64 v40, |v34|, s97
	v_exp_f32_e32 v40, v40
	v_add_f32_e32 v33, v33, v36
	v_max_f32_e64 v34, -v34, 0
	v_sub_f32_e32 v33, -0.5, v33
	v_add_f32_e32 v36, 1.0, v40
	v_cmp_gt_f32_e32 vcc, s33, v36
	v_mul_f32_e32 v33, 0x3fb8aa3b, v33
	v_exp_f32_e32 v33, v33
	v_cndmask_b32_e64 v40, 0, 32, vcc
	v_ldexp_f32 v36, v36, v40
	v_log_f32_e32 v36, v36
	s_nop 0
	v_mul_f32_e32 v40, 0x3f317217, v36
	v_fma_f32 v40, v36, s48, -v40
	v_fmac_f32_e32 v40, 0x3377d1cf, v36
	v_fmac_f32_e32 v40, 0x3f317217, v36
	v_cmp_lt_f32_e64 s[24:25], |v36|, s49
	s_nop 1
	v_cndmask_b32_e64 v36, v36, v40, s[24:25]
	v_cndmask_b32_e32 v40, 0, v176, vcc
	v_sub_f32_e32 v36, v36, v40
	v_cmp_gt_f32_e32 vcc, s33, v35
	v_add_f32_e32 v34, v34, v36
	v_sub_f32_e32 v34, -0.5, v34
	v_cndmask_b32_e64 v36, 0, 32, vcc
	v_ldexp_f32 v35, v35, v36
	v_log_f32_e32 v35, v35
	v_mul_f32_e32 v34, 0x3fb8aa3b, v34
	v_exp_f32_e32 v34, v34
	v_xor_b32_e32 v40, 0x80000000, v32
	v_mul_f32_e32 v36, 0x3f317217, v35
	v_fma_f32 v36, v35, s48, -v36
	v_fmac_f32_e32 v36, 0x3377d1cf, v35
	v_fmac_f32_e32 v36, 0x3f317217, v35
	v_cmp_lt_f32_e64 s[24:25], |v35|, s49
	s_nop 1
	v_cndmask_b32_e64 v35, v35, v36, s[24:25]
	v_cndmask_b32_e32 v36, 0, v176, vcc
	v_sub_f32_e32 v35, v35, v36
	v_add_f32_e32 v2, v2, v35
	v_sub_f32_e32 v2, -0.5, v2
	v_mul_f32_e32 v2, 0x3fb8aa3b, v2
	v_exp_f32_e32 v35, v2
	v_pk_add_f32 v[2:3], v[32:33], 0 neg_lo:[1,1] neg_hi:[1,1]
	v_xor_b32_e32 v36, 0x80000000, v33
	v_cvt_pk_bf16_f32 v2, v2, v3
	ds_write2st64_b32 v148, v0, v40 offset0:82 offset1:114
	ds_write2st64_b32 v150, v37, v36 offset0:82 offset1:114
	v_lshlrev_b32_e32 v36, 16, v2
	v_and_b32_e32 v37, 0xffff0000, v2
	v_pk_add_f32 v[32:33], v[32:33], v[36:37] neg_lo:[1,1] neg_hi:[1,1]
	v_pk_add_f32 v[36:37], v[34:35], 0 neg_lo:[1,1] neg_hi:[1,1]
	v_xor_b32_e32 v3, 0x80000000, v34
	v_xor_b32_e32 v0, 0x80000000, v35
	ds_write2st64_b32 v152, v38, v3 offset0:82 offset1:114
	ds_write2st64_b32 v154, v39, v0 offset0:82 offset1:114
	v_cvt_pk_bf16_f32 v3, v36, v37
	v_lshlrev_b32_e32 v36, 16, v3
	v_and_b32_e32 v37, 0xffff0000, v3
	v_pk_add_f32 v[34:35], v[34:35], v[36:37] neg_lo:[1,1] neg_hi:[1,1]
	ds_write_b64 v92, v[2:3]
	v_cvt_pk_bf16_f32 v2, v32, v33
	v_cvt_pk_bf16_f32 v3, v34, v35
	ds_write_b64 v93, v[2:3]
	s_waitcnt lgkmcnt(0)
	s_barrier
	ds_read_b128 v[36:39], v94 offset:29184
	ds_read_b128 v[32:35], v94 offset:20992
	ds_read_b128 v[44:47], v96 offset:17408
	ds_read_b128 v[218:221], v96 offset:17152
	ds_read_b128 v[40:43], v95
	ds_read_b128 v[222:225], v95 offset:256
	s_and_b64 s[24:25], s[4:5], exec
	s_cselect_b32 s24, s62, s63
	s_lshl_b32 s24, s24, 5
	s_waitcnt lgkmcnt(4)
	v_mul_f32_e32 v0, 0xbfb8aa3b, v32
	v_exp_f32_e32 v0, v0
	v_mul_f32_e32 v2, 0xbfb8aa3b, v33
	v_exp_f32_e32 v2, v2
	s_or_b32 s24, s60, s24
	v_add_f32_e32 v0, 1.0, v0
	v_rcp_f32_e32 v64, v0
	v_add_f32_e32 v0, 1.0, v2
	v_rcp_f32_e32 v65, v0
	s_mov_b32 s25, s61
	v_lshl_add_u64 v[58:59], s[24:25], 0, v[52:53]
	v_pk_add_f32 v[2:3], v[64:65], -1.0 op_sel_hi:[1,0]
	s_waitcnt lgkmcnt(2)
	v_pk_fma_f32 v[2:3], v[2:3], v[218:219], 1.0 op_sel_hi:[1,1,0]
	s_waitcnt lgkmcnt(0)
	v_pk_mul_f32 v[62:63], v[222:223], v[2:3]
	v_mul_f32_e32 v3, 0xbfb8aa3b, v35
	v_mul_f32_e32 v0, v40, v62
	v_fma_f32 v0, v44, v0, 0
	v_mul_f32_e32 v2, v41, v63
	v_fmac_f32_e32 v0, v45, v2
	v_mul_f32_e32 v2, 0xbfb8aa3b, v34
	ds_read_b128 v[32:35], v95 offset:512
	ds_read_b128 v[226:229], v96 offset:16896
	v_exp_f32_e32 v2, v2
	v_exp_f32_e32 v3, v3
	v_add_f32_e32 v2, 1.0, v2
	s_waitcnt lgkmcnt(0)
	v_pk_mul_f32 v[70:71], v[222:223], v[226:227]
	v_rcp_f32_e32 v66, v2
	v_add_f32_e32 v2, 1.0, v3
	v_pk_mul_f32 v[68:69], v[224:225], v[228:229]
	v_pk_mul_f32 v[44:45], v[70:71], v[70:71]
	v_rcp_f32_e32 v67, v2
	v_pk_mul_f32 v[2:3], v[68:69], v[68:69]
	v_add_f32_e32 v44, v44, v45
	v_add_f32_e32 v2, v44, v2
	v_add_f32_e32 v2, v2, v3
	s_nop 1
	v_add_f32_dpp v2, v2, v2 quad_perm:[1,0,3,2] row_mask:0xf bank_mask:0xf bound_ctrl:1
	s_nop 1
	v_add_f32_dpp v2, v2, v2 quad_perm:[2,3,0,1] row_mask:0xf bank_mask:0xf bound_ctrl:1
	s_nop 1
	v_add_f32_dpp v51, v2, v2 row_half_mirror row_mask:0xf bank_mask:0xf bound_ctrl:1
	v_pk_add_f32 v[2:3], v[66:67], -1.0 op_sel_hi:[1,0]
	s_nop 0
	v_pk_fma_f32 v[2:3], v[2:3], v[220:221], 1.0 op_sel_hi:[1,1,0]
	v_mov_b32_dpp v218, v51 row_mirror row_mask:0xf bank_mask:0xf bound_ctrl:1
	v_pk_mul_f32 v[60:61], v[224:225], v[2:3]
	s_nop 0
	v_mul_f32_e32 v2, v42, v60
	v_fmac_f32_e32 v0, v46, v2
	v_mul_f32_e32 v2, v43, v61
	v_fmac_f32_e32 v0, v47, v2
	s_nop 1
	v_add_f32_dpp v0, v0, v0 quad_perm:[1,0,3,2] row_mask:0xf bank_mask:0xf bound_ctrl:1
	s_nop 1
	v_add_f32_dpp v0, v0, v0 quad_perm:[2,3,0,1] row_mask:0xf bank_mask:0xf bound_ctrl:1
	s_nop 1
	v_add_f32_dpp v0, v0, v0 row_half_mirror row_mask:0xf bank_mask:0xf bound_ctrl:1
	s_nop 1
	v_mov_b32_dpp v2, v0 row_mirror row_mask:0xf bank_mask:0xf bound_ctrl:1
	s_and_saveexec_b64 s[24:25], s[6:7]
	s_cbranch_execz .LBB0_323
	v_add_f32_e32 v0, v0, v2
	v_lshlrev_b64 v[2:3], 5, v[58:59]
	v_lshl_add_u64 v[2:3], s[40:41], 0, v[2:3]
	global_store_dword v[2:3], v0, off

; __device__ void rwkv_chunk_phase(const Params& p, int l, LAS unsigned char* lds) {
;     ...
;             if (ci + 1 < 64 && rp_ == STG_REP - 1) { RW_LOAD(dir ? 62 - ci : ci + 1); }
.LBB0_325:
	s_or_b64 exec, exec, s[24:25]
	s_add_i32 s62, s63, 1
	s_cmp_eq_u32 s63, 63
	s_cbranch_scc1 .LBB0_331
	s_and_b64 s[24:25], s[4:5], exec
	s_cselect_b32 s24, s65, s62
	v_lshl_add_u32 v24, s24, 5, v52
	v_ashrrev_i32_e32 v25, 31, v24
	v_lshl_add_u64 v[2:3], s[60:61], 0, v[24:25]
	v_mad_u64_u32 v[44:45], s[24:25], v2, s46, v[54:55]
	v_mad_i32_i24 v45, v3, s46, v45
	global_load_dwordx4 v[8:11], v[44:45], off
	global_load_dwordx4 v[12:15], v[44:45], off offset:16
	v_mov_b32_e32 v2, v1
	v_mov_b32_e32 v3, v1
	v_mov_b32_e32 v0, v1
	v_mov_b64_e32 v[18:19], v[2:3]
	v_mov_b64_e32 v[22:23], v[2:3]
	v_cmp_lt_i32_e32 vcc, 0, v24
	v_mov_b64_e32 v[16:17], v[0:1]
	v_mov_b64_e32 v[20:21], v[0:1]
	s_and_saveexec_b64 s[24:25], vcc
	s_cbranch_execz .LBB0_328
	v_add_co_u32_e32 v2, vcc, 0xfffff240, v44
	s_nop 1
	v_addc_co_u32_e32 v3, vcc, -1, v45, vcc
	v_add_co_u32_e32 v20, vcc, 0xfffff250, v44
	s_nop 1
	v_addc_co_u32_e32 v21, vcc, -1, v45, vcc
	global_load_dwordx4 v[16:19], v[2:3], off
	s_nop 0
	global_load_dwordx4 v[20:23], v[20:21], off
.LBB0_328:
	s_or_b64 exec, exec, s[24:25]
	v_cmp_gt_i32_e32 vcc, s75, v24
	v_mov_b32_e32 v31, 0
	v_mov_b32_e32 v30, 0
	v_mov_b32_e32 v29, 0
	v_mov_b32_e32 v28, 0
	v_mov_b32_e32 v27, 0
	v_mov_b32_e32 v26, 0
	v_mov_b32_e32 v25, 0
	v_mov_b32_e32 v24, 0
	s_and_saveexec_b64 s[24:25], vcc
	s_cbranch_execz .LBB0_330
	global_load_dwordx4 v[24:27], v[44:45], off offset:3520
	global_load_dwordx4 v[28:31], v[44:45], off offset:3536

; #define LAS __attribute__((address_space(3)))
; __device__ void gla_chunk_phase(const Params& p, int l, LAS unsigned char* lds) {
;     ...
;         {   const int c = dir ? 31 : 0; const size_t tb = (size_t)b * SEQ_ + c * 64;
;             const bf16_t* zr = ZG + (tb + ltokm) * ZGC;
;             rq = *(const uint4*)(zr + h * 64 + lc8); rk = *(const uint4*)(zr + 256 + h * 64 + lc8); rv = *(const uint4*)(zr + 512 + h * 128 + vh * 64 + lc8);
;             if (tid < 128) rd = *(const uint4*)(ZG + (tb + dtokm) * ZGC + dncol + dc8); }
;     ...
;             {   const f32x4 b0 = *(const LAS f32x4*)(b_s + ltok * 64 + lc8), b1 = *(const LAS f32x4*)(b_s + ltok * 64 + lc8 + 4);
;                 const f32x4 d0 = *(const LAS f32x4*)(dk_s + lc8), d1 = *(const LAS f32x4*)(dk_s + lc8 + 4);
;                 float qv[8], kv[8], ktv[8];
; #pragma unroll
;                 for (int j = 0; j < 8; ++j) {
;                     const float bb = (j < 4) ? b0[j & 3] : b1[j & 3], dkj = (j < 4) ? d0[j & 3] : d1[j & 3];
;                     const float e = __expf(bb), einv = __builtin_amdgcn_rcpf(e);
;                     qv[j] = fq[j] * 0.125f * e; kv[j] = fk[j] * einv;
;                     ktv[j] = kv[j] * dkj;
.LBB0_430:
	s_or_b64 exec, exec, s[6:7]
	s_ashr_i32 s8, s40, 4
	s_and_b64 s[6:7], exec, s[76:77]
	s_movk_i32 s6, 0x610
	s_cselect_b32 s6, 0x600, s6
	s_ashr_i32 s9, s8, 31
	s_lshl_b64 s[92:93], s[8:9], 11
	s_and_b64 s[8:9], exec, s[76:77]
	v_cndmask_b32_e64 v54, v66, v64, s[76:77]
	s_cselect_b32 s86, 0, 0x7c0
	s_or_b64 s[8:9], s[92:93], s[86:87]
	v_ashrrev_i32_e32 v55, 31, v54
	v_lshl_add_u64 v[6:7], s[8:9], 0, v[54:55]
	v_mov_b64_e32 v[8:9], s[82:83]
	v_mad_u64_u32 v[8:9], s[10:11], v6, s47, v[8:9]
	v_mad_i32_i24 v9, v7, s47, v9
	s_lshl_b32 s86, s41, 7
	v_lshl_add_u64 v[6:7], v[8:9], 0, s[86:87]
	v_lshlrev_b32_e32 v0, 1, v46
	s_lshl_b32 s7, s40, 6
	v_lshl_add_u64 v[6:7], v[6:7], 0, v[0:1]
	s_lshl_b32 s10, s41, 8
	s_mov_b32 s11, s87
	s_and_b32 s7, s7, 64
	global_load_dwordx4 v[38:41], v[6:7], off
	global_load_dwordx4 v[30:33], v[6:7], off offset:512
	v_lshl_add_u64 v[6:7], v[8:9], 0, s[10:11]
	s_lshl_b32 s94, s7, 1
	s_mov_b32 s95, s87
	v_lshl_add_u64 v[6:7], v[6:7], 0, s[94:95]
	v_lshl_add_u64 v[6:7], v[6:7], 0, v[0:1]
	global_load_dwordx4 v[34:37], v[6:7], off offset:1024
	s_mov_b32 s7, s87
	v_mov_b64_e32 v[10:11], s[6:7]
	s_mov_b64 s[10:11], exec
	v_readlane_b32 s12, v254, 51
	v_readlane_b32 s13, v254, 52
	s_and_b64 s[12:13], s[10:11], s[12:13]
	s_xor_b64 s[10:11], s[12:13], s[10:11]
	s_mov_b64 exec, s[12:13]
	v_mov_b64_e32 v[10:11], s[6:7]
	s_or_saveexec_b64 s[10:11], s[10:11]
	v_mov_b32_e32 v6, v1
	v_mov_b32_e32 v7, v1
	v_cndmask_b32_e64 v114, v67, v65, s[76:77]
	s_lshl_b32 s22, s41, 6
	v_mov_b64_e32 v[8:9], v[6:7]
	s_xor_b64 exec, exec, s[10:11]
	s_cbranch_execz .LBB0_434
	v_or_b32_e32 v8, s8, v114
	v_mov_b64_e32 v[6:7], s[82:83]
	v_mad_u64_u32 v[6:7], s[12:13], v8, s47, v[6:7]
	v_mad_i32_i24 v7, s9, v177, v7
	s_lshl_b32 s6, s6, 1
	s_mov_b32 s7, s87
	v_lshl_add_u64 v[6:7], v[6:7], 0, s[6:7]
	v_mov_b32_e32 v53, v1
	v_lshl_add_u64 v[6:7], v[6:7], 0, v[52:53]
	global_load_dwordx4 v[6:9], v[6:7], off
.LBB0_434:
	s_or_b64 exec, exec, s[10:11]
	v_lshlrev_b32_e32 v10, 1, v10
	v_mov_b32_e32 v11, v1
	v_lshl_add_u64 v[58:59], v[48:49], 0, v[10:11]
	v_cndmask_b32_e64 v10, 0, 1, s[2:3]
	v_cndmask_b32_e64 v11, 0, 1, s[72:73]
	v_cndmask_b32_e64 v10, v11, v10, s[76:77]
	v_cndmask_b32_e64 v11, 0, 1, s[54:55]
	v_cndmask_b32_e64 v12, 0, 1, s[4:5]
	v_cndmask_b32_e64 v11, v12, v11, s[76:77]
	s_lshl_b32 s34, s86, 1
	v_and_b32_e32 v11, 1, v11
	s_add_u32 s6, s20, s34
	v_cmp_eq_u32_e64 s[8:9], 1, v11
	v_cndmask_b32_e64 v11, 0, 1, s[58:59]
	v_cndmask_b32_e64 v12, 0, 1, s[56:57]
	s_addc_u32 s7, s21, 0
	v_cndmask_b32_e64 v11, v12, v11, s[76:77]
	s_add_u32 s6, s6, s94
	v_and_b32_e32 v11, 1, v11
	s_addc_u32 s7, s7, 0
	v_cmp_eq_u32_e64 s[10:11], 1, v11
	v_cndmask_b32_e64 v11, 0, 1, s[62:63]
	v_cndmask_b32_e64 v12, 0, 1, s[60:61]
	v_lshl_add_u64 v[56:57], s[6:7], 0, v[0:1]
	v_and_b32_e32 v10, 1, v10
	s_lshr_b32 s6, s42, 1
	v_cndmask_b32_e64 v11, v12, v11, s[76:77]
	v_cmp_eq_u32_e32 vcc, 1, v10
	v_or_b32_e32 v10, s6, v80
	v_and_b32_e32 v11, 1, v11
	v_cmp_gt_i32_e64 s[6:7], v86, v10
	v_cmp_eq_u32_e64 s[12:13], 1, v11
	v_cmp_gt_i32_e64 s[14:15], v94, v10
	v_cndmask_b32_e64 v10, 0, 1, s[66:67]
	v_cndmask_b32_e64 v11, 0, 1, s[64:65]
	v_cndmask_b32_e64 v10, v11, v10, s[76:77]
	v_and_b32_e32 v10, 1, v10
	v_cmp_eq_u32_e64 s[16:17], 1, v10
	v_cndmask_b32_e64 v10, 0, 1, s[70:71]
	v_cndmask_b32_e64 v11, 0, 1, s[68:69]
	v_cndmask_b32_e64 v10, v11, v10, s[76:77]
	v_and_b32_e32 v10, 1, v10
	v_mov_b32_e32 v22, 0
	s_mov_b32 s41, 1
	v_lshl_add_u64 v[60:61], s[92:93], 0, v[54:55]
	v_cmp_eq_u32_e64 s[18:19], 1, v10
	s_mov_b32 s42, 30
	s_lshl_b32 s84, s22, 1
	v_mov_b32_e32 v23, v22
	v_mov_b32_e32 v24, v22
	v_mov_b32_e32 v25, v22
	v_mov_b32_e32 v26, v22
	v_mov_b32_e32 v27, v22
	v_mov_b32_e32 v28, v22
	v_mov_b32_e32 v29, v22
	s_waitcnt vmcnt(0)
	s_branch .LBB0_436
.LBB0_435:
	s_or_b64 exec, exec, s[20:21]
	s_waitcnt lgkmcnt(0)
	s_barrier
	s_waitcnt vmcnt(0)
	s_nop 0
	v_lshlrev_b32_e32 v44, 16, v38
	v_and_b32_e32 v45, 0xffff0000, v38
	v_lshlrev_b32_e32 v62, 16, v39
	v_and_b32_e32 v63, 0xffff0000, v39
	v_lshlrev_b32_e32 v120, 16, v40
	v_and_b32_e32 v121, 0xffff0000, v40
	v_lshlrev_b32_e32 v122, 16, v41
	v_and_b32_e32 v123, 0xffff0000, v41
	v_lshlrev_b32_e32 v124, 16, v30
	v_and_b32_e32 v125, 0xffff0000, v30
	v_lshlrev_b32_e32 v126, 16, v31
	v_and_b32_e32 v127, 0xffff0000, v31
	v_lshlrev_b32_e32 v128, 16, v32
	v_and_b32_e32 v129, 0xffff0000, v32
	v_lshlrev_b32_e32 v30, 16, v33
	v_and_b32_e32 v31, 0xffff0000, v33
	v_lshlrev_b32_e32 v53, 16, v34
	v_and_b32_e32 v115, 0xffff0000, v34
	v_lshlrev_b32_e32 v148, 16, v35
	v_and_b32_e32 v149, 0xffff0000, v35
	v_lshlrev_b32_e32 v150, 16, v36
	v_and_b32_e32 v151, 0xffff0000, v36
	v_lshlrev_b32_e32 v152, 16, v37
	v_and_b32_e32 v153, 0xffff0000, v37
	ds_read_b128 v[32:35], v76
	ds_read_b128 v[36:39], v76 offset:16
	ds_read_b128 v[40:43], v77
	ds_read_b128 v[116:119], v77 offset:16
	v_pk_mul_f32 v[44:45], v[44:45], s[74:75] op_sel_hi:[1,0]
	s_waitcnt lgkmcnt(3)
	v_mul_f32_e32 v32, 0x3fb8aa3b, v32
	v_mul_f32_e32 v33, 0x3fb8aa3b, v33
	v_exp_f32_e32 v32, v32
	v_exp_f32_e32 v33, v33
	v_mul_f32_e32 v34, 0x3fb8aa3b, v34
	v_mul_f32_e32 v35, 0x3fb8aa3b, v35
	v_rcp_f32_e32 v138, v32
	v_rcp_f32_e32 v139, v33
	v_exp_f32_e32 v34, v34
	v_exp_f32_e32 v35, v35
	s_waitcnt lgkmcnt(2)
; #define LAS __attribute__((address_space(3)))
; __device__ void gla_chunk_phase(const Params& p, int l, LAS unsigned char* lds) {
;     ...
;             {   const f32x4 b0 = *(const LAS f32x4*)(b_s + ltok * 64 + lc8), b1 = *(const LAS f32x4*)(b_s + ltok * 64 + lc8 + 4);
;                 const f32x4 d0 = *(const LAS f32x4*)(dk_s + lc8), d1 = *(const LAS f32x4*)(dk_s + lc8 + 4);
;                 float qv[8], kv[8], ktv[8];
; #pragma unroll
;                 for (int j = 0; j < 8; ++j) {
;                     const float bb = (j < 4) ? b0[j & 3] : b1[j & 3], dkj = (j < 4) ? d0[j & 3] : d1[j & 3];
;                     const float e = __expf(bb), einv = __builtin_amdgcn_rcpf(e);
;                     qv[j] = fq[j] * 0.125f * e; kv[j] = fk[j] * einv;
;                     ktv[j] = kv[j] * dkj;
;                 }
;                 const uint4 q4 = pack8(qv), k4 = pack8(kv), t4 = pack8(ktv), v4 = pack8(fv);
;                 *(LAS u32x4*)(qd + ltok * 72 + lc8) = (u32x4){q4.x, q4.y, q4.z, q4.w}; *(LAS u32x4*)(kd + ltok * 72 + lc8) = (u32x4){k4.x, k4.y, k4.z, k4.w};
;                 *(LAS u32x4*)(ktT + ltok * 72 + lc8) = (u32x4){t4.x, t4.y, t4.z, t4.w}; *(LAS u32x4*)(vT + ltok * 72 + lc8) = (u32x4){v4.x, v4.y, v4.z, v4.w}; }
;             LBAR();
;             f32x4 oacc[2] = {{0.f, 0.f, 0.f, 0.f}, {0.f, 0.f, 0.f, 0.f}};
;             {
;                 f32x4 sc[2] = {{0.f, 0.f, 0.f, 0.f}, {0.f, 0.f, 0.f, 0.f}};
;                 const f32x4 dkv = *(const LAS f32x4*)(dk_s + tr * 16 + quad * 4);
;                 sacc[0] *= dkv; sacc[1] *= dkv;
;                 const int arow = (tr * 16 + r16) * 72 + quad * 8;
; #pragma unroll
;                 for (int ks = 0; ks < 2; ++ks) {
;                     const bf16x8 a_kd = *(const LAS bf16x8*)(kd + arow + ks * 32), a_st = *(const LAS bf16x8*)(stT + arow + ks * 32), a_kt = trfrag(ktT, 72, ks * 32, tr * 16, lane);
; #pragma unroll
;                     for (int t = 0; t < 2; ++t) { const int brow = ((tcb + t) * 16 + r16) * 72 + ks * 32 + quad * 8;
;                         const bf16x8 b_qd = *(const LAS bf16x8*)(qd + brow), b_vT = trfrag(vT, 72, ks * 32, (tcb + t) * 16, lane);
;                         sc[t] = __builtin_amdgcn_mfma_f32_16x16x32_bf16(a_kd, b_qd, sc[t], 0, 0, 0);
;                         oacc[t] = __builtin_amdgcn_mfma_f32_16x16x32_bf16(a_st, b_qd, oacc[t], 0, 0, 0);
	v_mul_f32_e32 v36, 0x3fb8aa3b, v36
	v_mul_f32_e32 v37, 0x3fb8aa3b, v37
	v_pk_mul_f32 v[32:33], v[44:45], v[32:33]
	v_pk_mul_f32 v[44:45], v[138:139], v[124:125]
	v_rcp_f32_e32 v124, v34
	v_rcp_f32_e32 v125, v35
	v_exp_f32_e32 v36, v36
	v_exp_f32_e32 v37, v37
	v_pk_mul_f32 v[62:63], v[62:63], s[74:75] op_sel_hi:[1,0]
	v_mul_f32_e32 v38, 0x3fb8aa3b, v38
	v_mul_f32_e32 v39, 0x3fb8aa3b, v39
	v_pk_mul_f32 v[34:35], v[62:63], v[34:35]
	v_pk_mul_f32 v[62:63], v[124:125], v[126:127]
	v_rcp_f32_e32 v124, v36
	v_rcp_f32_e32 v125, v37
	v_exp_f32_e32 v38, v38
	v_exp_f32_e32 v39, v39
	v_pk_mul_f32 v[120:121], v[120:121], s[74:75] op_sel_hi:[1,0]
	v_pk_mul_f32 v[122:123], v[122:123], s[74:75] op_sel_hi:[1,0]
	v_pk_mul_f32 v[36:37], v[120:121], v[36:37]
	v_pk_mul_f32 v[120:121], v[124:125], v[128:129]
	v_rcp_f32_e32 v124, v38
	v_rcp_f32_e32 v125, v39
	v_pk_mul_f32 v[38:39], v[122:123], v[38:39]
	s_waitcnt lgkmcnt(1)
	v_pk_mul_f32 v[40:41], v[40:41], v[44:45]
	v_pk_mul_f32 v[42:43], v[42:43], v[62:63]
	v_pk_mul_f32 v[122:123], v[124:125], v[30:31]
	s_waitcnt lgkmcnt(0)
	v_pk_mul_f32 v[116:117], v[116:117], v[120:121]
	v_pk_mul_f32 v[118:119], v[118:119], v[122:123]
	v_cvt_pk_bf16_f32 v30, v32, v33
	v_cvt_pk_bf16_f32 v31, v34, v35
	v_cvt_pk_bf16_f32 v32, v36, v37
	v_cvt_pk_bf16_f32 v33, v38, v39
	v_cvt_pk_bf16_f32 v34, v44, v45
	v_cvt_pk_bf16_f32 v35, v62, v63
	v_cvt_pk_bf16_f32 v36, v120, v121
	v_cvt_pk_bf16_f32 v37, v122, v123
	v_cvt_pk_bf16_f32 v38, v40, v41
	v_cvt_pk_bf16_f32 v39, v42, v43
	v_cvt_pk_bf16_f32 v40, v116, v117
	v_cvt_pk_bf16_f32 v41, v118, v119
	v_cvt_pk_bf16_f32 v42, v53, v115
	v_cvt_pk_bf16_f32 v43, v148, v149
	v_cvt_pk_bf16_f32 v44, v150, v151
	v_cvt_pk_bf16_f32 v45, v152, v153
	ds_write_b128 v50, v[30:33] offset:16384
	ds_write_b128 v50, v[34:37] offset:25600
	ds_write_b128 v50, v[38:41] offset:34816
	ds_write_b128 v50, v[42:45] offset:44032
	s_waitcnt lgkmcnt(0)
	s_barrier
	ds_read_b128 v[30:33], v51
	v_add_u32_e32 v53, v79, v87
	v_add_u32_e32 v62, v81, v87
	v_add_u32_e32 v63, v81, v95
	v_add_u32_e32 v115, v79, v95
	s_waitcnt lgkmcnt(0)
	v_pk_mul_f32 v[24:25], v[24:25], v[32:33]
	v_pk_mul_f32 v[22:23], v[22:23], v[30:31]
	v_pk_mul_f32 v[28:29], v[28:29], v[32:33]
	v_pk_mul_f32 v[26:27], v[26:27], v[30:31]
	ds_read_b128 v[30:33], v78 offset:25600
	ds_read_b128 v[34:37], v78 offset:62464
	ds_read_b64_tr_b16 v[38:39], v88 offset:34816
	ds_read_b64_tr_b16 v[40:41], v88 offset:35392
	ds_read_b128 v[42:45], v53 offset:16384
	ds_read_b64_tr_b16 v[116:117], v89 offset:44032
	ds_read_b64_tr_b16 v[118:119], v89 offset:44608
	s_waitcnt lgkmcnt(0)
	v_mfma_f32_16x16x32_bf16 v[22:25], v[38:41], v[116:119], v[22:25]
	ds_read_b128 v[116:119], v110 offset:16384
	ds_read_b64_tr_b16 v[124:125], v90 offset:44032
	ds_read_b64_tr_b16 v[126:127], v90 offset:44608
	s_add_i32 s22, s41, -1
	s_add_i32 s23, s42, 1
	v_mfma_f32_16x16x32_bf16 v[120:123], v[30:33], v[42:45], 0
	s_and_b64 s[20:21], exec, s[76:77]
	s_cselect_b32 s20, s22, s23
	s_lshl_b32 s86, s20, 6
	v_mfma_f32_16x16x32_bf16 v[42:45], v[34:37], v[42:45], 0
	s_add_i32 s42, s42, -1
	s_add_i32 s41, s41, 1
	s_cmp_eq_u32 s42, -2
	s_waitcnt lgkmcnt(2)
	v_mfma_f32_16x16x32_bf16 v[30:33], v[30:33], v[116:119], 0
	v_mfma_f32_16x16x32_bf16 v[34:37], v[34:37], v[116:119], 0
	s_waitcnt lgkmcnt(0)
	v_mfma_f32_16x16x32_bf16 v[26:29], v[38:41], v[124:127], v[26:29]
	ds_read_b128 v[38:41], v78 offset:25664
	ds_read_b128 v[116:119], v78 offset:62528
	ds_read_b64_tr_b16 v[124:125], v91 offset:34816
	ds_read_b64_tr_b16 v[126:127], v91 offset:35392
	ds_read_b128 v[148:151], v53 offset:16448
	ds_read_b64_tr_b16 v[152:153], v92 offset:44032
	ds_read_b64_tr_b16 v[154:155], v92 offset:44608
	s_waitcnt lgkmcnt(2)
	v_mfma_f32_16x16x32_bf16 v[120:123], v[38:41], v[148:151], v[120:123]
	v_mfma_f32_16x16x32_bf16 v[42:45], v[116:119], v[148:151], v[42:45]
	s_waitcnt lgkmcnt(0)
	v_mfma_f32_16x16x32_bf16 v[22:25], v[124:127], v[152:155], v[22:25]
	ds_read_b128 v[148:151], v110 offset:16448
	ds_read_b64_tr_b16 v[152:153], v93 offset:44032
	ds_read_b64_tr_b16 v[154:155], v93 offset:44608
	s_waitcnt lgkmcnt(2)
	v_mfma_f32_16x16x32_bf16 v[30:33], v[38:41], v[148:151], v[30:33]
	v_cndmask_b32_e32 v38, 0, v120, vcc
	v_cndmask_b32_e64 v39, 0, v121, s[6:7]
	v_cndmask_b32_e64 v40, 0, v122, s[8:9]
	v_cndmask_b32_e64 v41, 0, v123, s[10:11]
	v_cvt_pk_bf16_f32 v38, v38, v39
	s_nop 2
	v_cndmask_b32_e64 v30, 0, v30, s[12:13]
	v_cndmask_b32_e64 v31, 0, v31, s[14:15]
	v_cndmask_b32_e64 v32, 0, v32, s[16:17]
	v_cndmask_b32_e64 v33, 0, v33, s[18:19]
	v_cvt_pk_bf16_f32 v39, v40, v41
	v_cvt_pk_bf16_f32 v30, v30, v31
	v_cvt_pk_bf16_f32 v31, v32, v33
	ds_write_b64 v62, v[38:39] offset:53248
	ds_write_b64 v63, v[30:31] offset:53248
	s_waitcnt lgkmcnt(0)
	s_barrier
	ds_read_b64_tr_b16 v[30:31], v111 offset:44032
	ds_read_b64_tr_b16 v[32:33], v111 offset:44608
	ds_read_b128 v[38:41], v53 offset:53248
	s_waitcnt lgkmcnt(0)
	v_mfma_f32_16x16x32_bf16 v[38:41], v[30:33], v[38:41], v[42:45]
	s_nop 2
	ds_read_b128 v[42:45], v115 offset:53248
	v_mfma_f32_16x16x32_bf16 v[34:37], v[116:119], v[148:151], v[34:37]
	s_waitcnt lgkmcnt(0)
	v_mfma_f32_16x16x32_bf16 v[30:33], v[30:33], v[42:45], v[34:37]
	s_nop 5
	ds_read_b64_tr_b16 v[34:35], v111 offset:48640
	ds_read_b64_tr_b16 v[36:37], v111 offset:49216
	ds_read_b128 v[42:45], v53 offset:53312
	s_waitcnt lgkmcnt(0)
	v_mfma_f32_16x16x32_bf16 v[38:41], v[34:37], v[42:45], v[38:41]
	ds_read_b128 v[42:45], v115 offset:53312
	v_mfma_f32_16x16x32_bf16 v[26:29], v[124:127], v[152:155], v[26:29]
	s_nop 5
	ds_write_b128 v112, v[38:41]
	v_mov_b64_e32 v[38:39], v[10:11]
	v_mov_b64_e32 v[40:41], v[12:13]
	s_waitcnt lgkmcnt(1)
	v_mfma_f32_16x16x32_bf16 v[30:33], v[34:37], v[42:45], v[30:33]
	v_cvt_pk_bf16_f32 v34, v22, v23
	v_cvt_pk_bf16_f32 v35, v24, v25
	ds_write_b64 v62, v[34:35] offset:62464
	s_nop 4
	ds_write_b128 v113, v[30:33]
	v_cvt_pk_bf16_f32 v30, v26, v27
	v_cvt_pk_bf16_f32 v31, v28, v29
	ds_write_b64 v63, v[30:31] offset:62464
	s_waitcnt lgkmcnt(0)
	s_barrier
	ds_read_b128 v[30:33], v82
	ds_read_b128 v[34:37], v82 offset:16
	s_waitcnt lgkmcnt(1)
	v_cvt_pk_bf16_f32 v30, v30, v31
	v_cvt_pk_bf16_f32 v31, v32, v33
	s_waitcnt lgkmcnt(0)
	v_cvt_pk_bf16_f32 v32, v34, v35
	v_lshl_add_u64 v[34:35], v[60:61], 0, s[86:87]
	v_lshlrev_b64 v[34:35], 10, v[34:35]
	v_cvt_pk_bf16_f32 v33, v36, v37
	v_lshl_add_u64 v[34:35], v[56:57], 0, v[34:35]
	global_store_dwordx4 v[34:35], v[30:33], off
	v_mov_b64_e32 v[34:35], v[18:19]
	v_mov_b64_e32 v[36:37], v[20:21]
	v_mov_b64_e32 v[30:31], v[14:15]
	v_mov_b64_e32 v[32:33], v[16:17]
	s_cbranch_scc1 .LBB0_397
; #define LAS __attribute__((address_space(3)))
; #define LBAR() do { asm volatile("s_waitcnt lgkmcnt(0)" ::: "memory"); __builtin_amdgcn_s_barrier(); asm volatile("" ::: "memory"); } while (0)
; __device__ void gla_chunk_phase(const Params& p, int l, LAS unsigned char* lds) {
;     ...
;             LBAR();
;             if (tid < 128) *(LAS u32x4*)(dnA + dtok * 40 + dc8) = (u32x4){rd.x, rd.y, rd.z, rd.w};
;             float fq[8], fk[8], fv[8];
;             unpack8(rq, fq); unpack8(rk, fk); unpack8(rv, fv);
;             if (ci + 1 < 32) {
;                 const int cn = dir ? 30 - ci : ci + 1; const size_t tb = (size_t)b * SEQ_ + cn * 64;
;                 const bf16_t* zr = ZG + (tb + ltokm) * ZGC;
;                 rq = *(const uint4*)(zr + h * 64 + lc8); rk = *(const uint4*)(zr + 256 + h * 64 + lc8); rv = *(const uint4*)(zr + 512 + h * 128 + vh * 64 + lc8);
;                 if (tid < 128) rd = *(const uint4*)(ZG + (tb + dtokm) * ZGC + dncol + dc8); }
.LBB0_436:
	s_waitcnt lgkmcnt(0)
	s_barrier
	s_and_saveexec_b64 s[20:21], s[44:45]
	s_cbranch_execz .LBB0_438
	s_waitcnt vmcnt(1) lgkmcnt(0)
	ds_write_b128 v104, v[6:9]
.LBB0_438:
	s_or_b64 exec, exec, s[20:21]
	s_cmp_eq_u32 s42, -1
	s_cbranch_scc1 .LBB0_442
	s_and_b64 s[20:21], exec, s[76:77]
	s_cselect_b32 s20, s41, s42
	s_lshl_b32 s20, s20, 6
	s_add_u32 s20, s92, s20
	s_addc_u32 s21, s93, 0
	v_lshl_add_u64 v[10:11], s[20:21], 0, v[54:55]
	v_mov_b64_e32 v[12:13], s[82:83]
	v_mad_u64_u32 v[18:19], s[22:23], v10, s47, v[12:13]
	v_mad_i32_i24 v19, v11, s47, v19
	s_mov_b32 s85, s87
	s_mov_b32 s35, s87
	v_lshl_add_u64 v[10:11], v[18:19], 0, s[84:85]
	v_lshl_add_u64 v[18:19], v[18:19], 0, s[34:35]
	s_mov_b32 s95, s87
	v_lshl_add_u64 v[18:19], v[18:19], 0, s[94:95]
	v_lshl_add_u64 v[14:15], v[10:11], 0, v[0:1]
	v_lshl_add_u64 v[18:19], v[18:19], 0, v[0:1]
	global_load_dwordx4 v[10:13], v[14:15], off
	s_nop 0
	global_load_dwordx4 v[14:17], v[14:15], off offset:512
	s_nop 0
	global_load_dwordx4 v[18:21], v[18:19], off offset:1024
	s_and_saveexec_b64 s[22:23], s[44:45]
	s_cbranch_execz .LBB0_441
	s_waitcnt lgkmcnt(0)
	v_or_b32_e32 v6, s20, v114
	v_mad_u64_u32 v[6:7], s[24:25], v6, s47, v[58:59]
	v_mad_i32_i24 v7, s21, v177, v7
	global_load_dwordx4 v[6:9], v[6:7], off
